# speedup vs baseline: 1.0100x; 1.0091x over previous
; __device__ __forceinline__ void norm_fix(f32x4 (&acc)[4][4], const float* rowss, const float* shW, int N, int brow, int bcol,
;                                          int wr, int wc, int fr, int fq) {
;   int mr = brow >> 12;
;   float sw[4];
; #pragma unroll
;   for (int n = 0; n < 4; n++) sw[n] = shW[(size_t)mr * N + bcol + (n >> 1) * 128 + wc * 32 + (n & 1) * 16 + fr];
; #pragma unroll
;   for (int m = 0; m < 4; m++)
; #pragma unroll
;     for (int j = 0; j < 4; j++) {
;       float rs = rsqrtf(rowss[brow + wr * 64 + m * 16 + fq * 4 + j] * (1.f / D) + 1e-6f);
; #pragma unroll
;       for (int n = 0; n < 4; n++) acc[m][n][j] = acc[m][n][j] * rs + sw[n];
;     }
; }
.LBB0_667:
	s_ashr_i32 s2, s36, 12
	s_mul_hi_i32 s3, s2, 0x5800
	s_mulk_i32 s2, 0x5800
	s_add_u32 s6, s19, s2
	s_addc_u32 s7, s21, s3
	s_lshl_b64 s[2:3], s[30:31], 2
	s_add_u32 s2, s6, s2
	s_addc_u32 s3, s7, s3
	s_lshl_b32 s6, s17, 2
	s_add_u32 s2, s2, s6
	v_ashrrev_i32_e32 v79, 31, v78
	s_addc_u32 s3, s3, 0
	v_lshl_add_u64 v[64:65], v[78:79], 2, s[0:1]
	global_load_dword v96, v179, s[2:3]
	global_load_dword v94, v179, s[2:3] offset:64
	global_load_dword v92, v179, s[2:3] offset:512
	global_load_dword v90, v179, s[2:3] offset:576
	v_mov_b64_e32 v[98:99], s[18:19]
	global_load_dwordx4 v[184:187], v[64:65], off offset:64
	global_load_dwordx4 v[188:191], v[64:65], off offset:128
	global_load_dwordx4 v[192:195], v[64:65], off offset:192
	global_load_dwordx4 v[64:67], v[64:65], off
	v_add_u32_e32 v84, 16, v78
	v_add_u32_e32 v76, 17, v78
	v_ashrrev_i32_e32 v85, 31, v84
	v_ashrrev_i32_e32 v77, 31, v76
	v_add_u32_e32 v88, 18, v78
	v_add_u32_e32 v86, 19, v78
	v_add_u32_e32 v80, 32, v78
	v_ashrrev_i32_e32 v89, 31, v88
	v_ashrrev_i32_e32 v87, 31, v86
	v_ashrrev_i32_e32 v81, 31, v80
	v_add_u32_e32 v72, 33, v78
	v_ashrrev_i32_e32 v73, 31, v72
	v_add_u32_e32 v82, 34, v78
	v_add_u32_e32 v74, 35, v78
	v_ashrrev_i32_e32 v83, 31, v82
	v_ashrrev_i32_e32 v75, 31, v74
	s_waitcnt vmcnt(0)
	v_pk_fma_f32 v[64:65], v[64:65], s[16:17], v[98:99] op_sel_hi:[1,0,0]
	s_nop 0
	v_mul_f32_e32 v68, 0x4b800000, v64
	v_cmp_gt_f32_e64 s[6:7], s54, v64
	v_cmp_gt_f32_e32 vcc, s54, v65
	v_pk_fma_f32 v[66:67], v[66:67], s[16:17], v[98:99] op_sel_hi:[1,0,0]
	v_cndmask_b32_e64 v64, v64, v68, s[6:7]
	v_mul_f32_e32 v68, 0x4b800000, v65
	v_cndmask_b32_e32 v65, v65, v68, vcc
	v_rsq_f32_e32 v64, v64
	v_rsq_f32_e32 v65, v65
	s_nop 0
	v_pk_mul_f32 v[68:69], v[64:65], s[20:21] op_sel_hi:[1,0]
	s_nop 0
	v_cndmask_b32_e64 v64, v64, v68, s[6:7]
	v_mul_f32_e32 v68, 0x4b800000, v66
	v_cmp_gt_f32_e64 s[6:7], s54, v66
	v_cndmask_b32_e32 v65, v65, v69, vcc
	v_cmp_gt_f32_e32 vcc, s54, v67
	v_cndmask_b32_e64 v66, v66, v68, s[6:7]
	v_mul_f32_e32 v68, 0x4b800000, v67
	v_cndmask_b32_e32 v67, v67, v68, vcc
	v_rsq_f32_e32 v66, v66
	v_rsq_f32_e32 v67, v67
	v_pk_fma_f32 v[56:57], v[56:57], v[64:65], v[96:97] op_sel_hi:[1,1,0]
	v_pk_fma_f32 v[60:61], v[60:61], v[64:65], v[94:95] op_sel_hi:[1,1,0]
	v_pk_fma_f32 v[48:49], v[48:49], v[64:65], v[92:93] op_sel_hi:[1,1,0]
	v_pk_mul_f32 v[68:69], v[66:67], s[20:21] op_sel_hi:[1,0]
	v_pk_fma_f32 v[52:53], v[52:53], v[64:65], v[90:91] op_sel_hi:[1,1,0]
	v_cndmask_b32_e32 v67, v67, v69, vcc
	v_cndmask_b32_e64 v66, v66, v68, s[6:7]
	v_pk_fma_f32 v[58:59], v[58:59], v[66:67], v[96:97] op_sel_hi:[1,1,0]
	v_pk_fma_f32 v[62:63], v[62:63], v[66:67], v[94:95] op_sel_hi:[1,1,0]
	v_pk_fma_f32 v[50:51], v[50:51], v[66:67], v[92:93] op_sel_hi:[1,1,0]
	v_pk_fma_f32 v[54:55], v[54:55], v[66:67], v[90:91] op_sel_hi:[1,1,0]
	v_lshl_add_u64 v[64:65], v[84:85], 2, s[0:1]
	v_lshl_add_u64 v[66:67], v[76:77], 2, s[0:1]
	v_mov_b32_e32 v64, v184
	v_lshl_add_u64 v[68:69], v[86:87], 2, s[0:1]
	v_mov_b32_e32 v65, v185
	s_waitcnt vmcnt(0)
	v_pk_fma_f32 v[64:65], v[64:65], s[16:17], v[98:99] op_sel_hi:[1,0,0]
	s_nop 0
	v_mul_f32_e32 v66, 0x4b800000, v64
	v_cmp_gt_f32_e64 s[6:7], s54, v64
	v_cmp_gt_f32_e32 vcc, s54, v65
	s_nop 0
	v_cndmask_b32_e64 v64, v64, v66, s[6:7]
	v_mul_f32_e32 v66, 0x4b800000, v65
	v_cndmask_b32_e32 v65, v65, v66, vcc
	v_rsq_f32_e32 v64, v64
	v_rsq_f32_e32 v65, v65
	s_nop 0
	v_pk_mul_f32 v[66:67], v[64:65], s[20:21] op_sel_hi:[1,0]
	s_nop 0
	v_cndmask_b32_e32 v65, v65, v67, vcc
	v_cndmask_b32_e64 v64, v64, v66, s[6:7]
	v_lshl_add_u64 v[66:67], v[88:89], 2, s[0:1]
	v_pk_fma_f32 v[40:41], v[40:41], v[64:65], v[96:97] op_sel_hi:[1,1,0]
	v_pk_fma_f32 v[44:45], v[44:45], v[64:65], v[94:95] op_sel_hi:[1,1,0]
	v_pk_fma_f32 v[32:33], v[32:33], v[64:65], v[92:93] op_sel_hi:[1,1,0]
	v_pk_fma_f32 v[36:37], v[36:37], v[64:65], v[90:91] op_sel_hi:[1,1,0]
	v_lshl_add_u64 v[64:65], v[80:81], 2, s[0:1]
	v_mov_b32_e32 v66, v186
	s_nop 0
	v_mov_b32_e32 v64, v188
	s_nop 0
	v_mov_b32_e32 v67, v187
	s_waitcnt vmcnt(0)
; __device__ __forceinline__ void norm_fix(f32x4 (&acc)[4][4], const float* rowss, const float* shW, int N, int brow, int bcol,
;                                          int wr, int wc, int fr, int fq) {
;   int mr = brow >> 12;
;   float sw[4];
; #pragma unroll
;   for (int n = 0; n < 4; n++) sw[n] = shW[(size_t)mr * N + bcol + (n >> 1) * 128 + wc * 32 + (n & 1) * 16 + fr];
; #pragma unroll
;   for (int m = 0; m < 4; m++)
; #pragma unroll
;     for (int j = 0; j < 4; j++) {
;       float rs = rsqrtf(rowss[brow + wr * 64 + m * 16 + fq * 4 + j] * (1.f / D) + 1e-6f);
; #pragma unroll
;       for (int n = 0; n < 4; n++) acc[m][n][j] = acc[m][n][j] * rs + sw[n];
;     }
; }
	v_pk_fma_f32 v[66:67], v[66:67], s[16:17], v[98:99] op_sel_hi:[1,0,0]
	s_nop 0
	v_mul_f32_e32 v68, 0x4b800000, v66
	v_cmp_gt_f32_e64 s[6:7], s54, v66
	v_cmp_gt_f32_e32 vcc, s54, v67
	s_nop 0
	v_cndmask_b32_e64 v66, v66, v68, s[6:7]
	v_mul_f32_e32 v68, 0x4b800000, v67
	v_cndmask_b32_e32 v67, v67, v68, vcc
	v_rsq_f32_e32 v66, v66
	v_rsq_f32_e32 v67, v67
	s_nop 0
	v_pk_mul_f32 v[68:69], v[66:67], s[20:21] op_sel_hi:[1,0]
	s_nop 0
	v_cndmask_b32_e32 v67, v67, v69, vcc
	v_cndmask_b32_e64 v66, v66, v68, s[6:7]
	v_pk_fma_f32 v[42:43], v[42:43], v[66:67], v[96:97] op_sel_hi:[1,1,0]
	v_pk_fma_f32 v[46:47], v[46:47], v[66:67], v[94:95] op_sel_hi:[1,1,0]
	v_pk_fma_f32 v[34:35], v[34:35], v[66:67], v[92:93] op_sel_hi:[1,1,0]
	v_pk_fma_f32 v[38:39], v[38:39], v[66:67], v[90:91] op_sel_hi:[1,1,0]
	v_lshl_add_u64 v[66:67], v[72:73], 2, s[0:1]
	v_mov_b32_e32 v65, v189
	v_lshl_add_u64 v[68:69], v[74:75], 2, s[0:1]
	s_waitcnt vmcnt(0)
	v_pk_fma_f32 v[64:65], v[64:65], s[16:17], v[98:99] op_sel_hi:[1,0,0]
	s_nop 0
	v_mul_f32_e32 v66, 0x4b800000, v64
	v_cmp_gt_f32_e64 s[6:7], s54, v64
	v_cmp_gt_f32_e32 vcc, s54, v65
	s_nop 0
	v_cndmask_b32_e64 v64, v64, v66, s[6:7]
	v_mul_f32_e32 v66, 0x4b800000, v65
	v_cndmask_b32_e32 v65, v65, v66, vcc
	v_rsq_f32_e32 v64, v64
	v_rsq_f32_e32 v65, v65
	s_nop 0
	v_pk_mul_f32 v[66:67], v[64:65], s[20:21] op_sel_hi:[1,0]
	s_nop 0
	v_cndmask_b32_e32 v65, v65, v67, vcc
	v_cndmask_b32_e64 v64, v64, v66, s[6:7]
	v_lshl_add_u64 v[66:67], v[82:83], 2, s[0:1]
	v_mov_b32_e32 v66, v190
	v_pk_fma_f32 v[24:25], v[24:25], v[64:65], v[96:97] op_sel_hi:[1,1,0]
	v_mov_b32_e32 v67, v191
	v_pk_fma_f32 v[28:29], v[28:29], v[64:65], v[94:95] op_sel_hi:[1,1,0]
	v_pk_fma_f32 v[16:17], v[16:17], v[64:65], v[92:93] op_sel_hi:[1,1,0]
	v_pk_fma_f32 v[20:21], v[20:21], v[64:65], v[90:91] op_sel_hi:[1,1,0]
	s_waitcnt vmcnt(0)
	v_pk_fma_f32 v[66:67], v[66:67], s[16:17], v[98:99] op_sel_hi:[1,0,0]
	s_nop 0
	v_mul_f32_e32 v68, 0x4b800000, v66
	v_cmp_gt_f32_e64 s[6:7], s54, v66
	v_cmp_gt_f32_e32 vcc, s54, v67
	s_nop 0
	v_cndmask_b32_e64 v66, v66, v68, s[6:7]
	v_mul_f32_e32 v68, 0x4b800000, v67
	v_cndmask_b32_e32 v67, v67, v68, vcc
	v_rsq_f32_e32 v66, v66
	v_rsq_f32_e32 v67, v67
	s_nop 0
	v_pk_mul_f32 v[68:69], v[66:67], s[20:21] op_sel_hi:[1,0]
	s_nop 0
	v_cndmask_b32_e64 v66, v66, v68, s[6:7]
	v_add_u32_e32 v68, 48, v78
	v_cndmask_b32_e32 v67, v67, v69, vcc
	v_ashrrev_i32_e32 v69, 31, v68
	v_lshl_add_u64 v[64:65], v[68:69], 2, s[0:1]
	v_pk_fma_f32 v[26:27], v[26:27], v[66:67], v[96:97] op_sel_hi:[1,1,0]
	v_pk_fma_f32 v[30:31], v[30:31], v[66:67], v[94:95] op_sel_hi:[1,1,0]
	v_pk_fma_f32 v[18:19], v[18:19], v[66:67], v[92:93] op_sel_hi:[1,1,0]
	v_pk_fma_f32 v[22:23], v[22:23], v[66:67], v[90:91] op_sel_hi:[1,1,0]
	v_mov_b32_e32 v66, v192
	v_add_u32_e32 v64, 49, v78
	v_ashrrev_i32_e32 v65, 31, v64
	v_lshl_add_u64 v[70:71], v[64:65], 2, s[0:1]
	v_mov_b32_e32 v67, v193
	s_waitcnt vmcnt(0)
	v_pk_fma_f32 v[66:67], v[66:67], s[16:17], v[98:99] op_sel_hi:[1,0,0]
	s_nop 0
	v_mul_f32_e32 v70, 0x4b800000, v66
	v_cmp_gt_f32_e64 s[6:7], s54, v66
	v_cmp_gt_f32_e32 vcc, s54, v67
	s_nop 0
	v_cndmask_b32_e64 v66, v66, v70, s[6:7]
	v_mul_f32_e32 v70, 0x4b800000, v67
	v_cndmask_b32_e32 v67, v67, v70, vcc
	v_rsq_f32_e32 v66, v66
	v_rsq_f32_e32 v67, v67
	s_nop 0
	v_pk_mul_f32 v[70:71], v[66:67], s[20:21] op_sel_hi:[1,0]
	s_nop 0
	v_cndmask_b32_e64 v100, v66, v70, s[6:7]
	v_add_u32_e32 v70, 50, v78
	v_cndmask_b32_e32 v101, v67, v71, vcc
	v_ashrrev_i32_e32 v71, 31, v70
	v_lshl_add_u64 v[66:67], v[70:71], 2, s[0:1]
	v_mov_b32_e32 v102, v194
	v_add_u32_e32 v66, 51, v78
	v_ashrrev_i32_e32 v67, 31, v66
	v_lshl_add_u64 v[104:105], v[66:67], 2, s[0:1]
	v_mov_b32_e32 v103, v195
	v_pk_fma_f32 v[8:9], v[8:9], v[100:101], v[96:97] op_sel_hi:[1,1,0]
	v_pk_fma_f32 v[12:13], v[12:13], v[100:101], v[94:95] op_sel_hi:[1,1,0]
	v_pk_fma_f32 v[0:1], v[0:1], v[100:101], v[92:93] op_sel_hi:[1,1,0]
	s_waitcnt vmcnt(0)
	v_pk_fma_f32 v[98:99], v[102:103], s[16:17], v[98:99] op_sel_hi:[1,0,0]
	s_nop 0
	v_mul_f32_e32 v91, 0x4b800000, v98
	v_cmp_gt_f32_e64 s[6:7], s54, v98
	v_cmp_gt_f32_e32 vcc, s54, v99
	s_nop 0
	v_cndmask_b32_e64 v91, v98, v91, s[6:7]
	v_rsq_f32_e32 v98, v91
	v_mul_f32_e32 v91, 0x4b800000, v99
	v_cndmask_b32_e32 v91, v99, v91, vcc
	v_rsq_f32_e32 v99, v91
	v_pk_fma_f32 v[4:5], v[4:5], v[100:101], v[90:91] op_sel_hi:[1,1,0]
	v_pk_mul_f32 v[102:103], v[98:99], s[20:21] op_sel_hi:[1,0]
	s_nop 0
	v_cndmask_b32_e32 v99, v99, v103, vcc
	v_cndmask_b32_e64 v98, v98, v102, s[6:7]
	v_pk_fma_f32 v[10:11], v[10:11], v[98:99], v[96:97] op_sel_hi:[1,1,0]
	v_pk_fma_f32 v[14:15], v[14:15], v[98:99], v[94:95] op_sel_hi:[1,1,0]
	v_pk_fma_f32 v[2:3], v[2:3], v[98:99], v[92:93] op_sel_hi:[1,1,0]
	v_pk_fma_f32 v[6:7], v[6:7], v[98:99], v[90:91] op_sel_hi:[1,1,0]
	v_mov_b64_e32 v[90:91], v[78:79]

; __device__ __forceinline__ void norm_fix(f32x4 (&acc)[4][4], const float* rowss, const float* shW, int N, int brow, int bcol,
;                                          int wr, int wc, int fr, int fq) {
;   int mr = brow >> 12;
;   float sw[4];
; #pragma unroll
;   for (int n = 0; n < 4; n++) sw[n] = shW[(size_t)mr * N + bcol + (n >> 1) * 128 + wc * 32 + (n & 1) * 16 + fr];
; #pragma unroll
;   for (int m = 0; m < 4; m++)
; #pragma unroll
;     for (int j = 0; j < 4; j++) {
;       float rs = rsqrtf(rowss[brow + wr * 64 + m * 16 + fq * 4 + j] * (1.f / D) + 1e-6f);
; #pragma unroll
;       for (int n = 0; n < 4; n++) acc[m][n][j] = acc[m][n][j] * rs + sw[n];
;     }
; }
.LBB0_682:
	s_ashr_i32 s2, s34, 12
	s_mul_hi_i32 s3, s2, 0x5800
	s_mulk_i32 s2, 0x5800
	s_add_u32 s6, s19, s2
	s_addc_u32 s7, s21, s3
	s_lshl_b64 s[2:3], s[30:31], 2
	s_add_u32 s2, s6, s2
	s_addc_u32 s3, s7, s3
	s_lshl_b32 s6, s17, 2
	s_add_u32 s2, s2, s6
	v_ashrrev_i32_e32 v155, 31, v154
	s_addc_u32 s3, s3, 0
	v_lshl_add_u64 v[140:141], v[154:155], 2, s[0:1]
	global_load_dword v170, v179, s[2:3]
	global_load_dword v168, v179, s[2:3] offset:64
	global_load_dword v166, v179, s[2:3] offset:512
	global_load_dword v138, v179, s[2:3] offset:576
	v_mov_b64_e32 v[172:173], s[18:19]
	global_load_dwordx4 v[184:187], v[140:141], off offset:64
	global_load_dwordx4 v[188:191], v[140:141], off offset:128
	global_load_dwordx4 v[192:195], v[140:141], off offset:192
	global_load_dwordx4 v[140:143], v[140:141], off
	v_add_u32_e32 v160, 16, v154
	v_add_u32_e32 v152, 17, v154
	v_ashrrev_i32_e32 v161, 31, v160
	v_ashrrev_i32_e32 v153, 31, v152
	v_add_u32_e32 v164, 18, v154
	v_add_u32_e32 v162, 19, v154
	v_ashrrev_i32_e32 v165, 31, v164
	v_ashrrev_i32_e32 v163, 31, v162
	v_add_u32_e32 v156, 32, v154
	v_add_u32_e32 v148, 33, v154
	v_ashrrev_i32_e32 v157, 31, v156
	v_ashrrev_i32_e32 v149, 31, v148
	v_add_u32_e32 v158, 34, v154
	v_add_u32_e32 v150, 35, v154
	v_ashrrev_i32_e32 v159, 31, v158
	v_ashrrev_i32_e32 v151, 31, v150
	s_waitcnt vmcnt(0)
	v_pk_fma_f32 v[140:141], v[140:141], s[16:17], v[172:173] op_sel_hi:[1,0,0]
	s_nop 0
	v_mul_f32_e32 v139, 0x4b800000, v140
	v_cmp_gt_f32_e64 s[6:7], s54, v140
	v_cmp_gt_f32_e32 vcc, s54, v141
	v_pk_fma_f32 v[142:143], v[142:143], s[16:17], v[172:173] op_sel_hi:[1,0,0]
	v_cndmask_b32_e64 v139, v140, v139, s[6:7]
	v_rsq_f32_e32 v140, v139
	v_mul_f32_e32 v139, 0x4b800000, v141
	v_cndmask_b32_e32 v139, v141, v139, vcc
	v_rsq_f32_e32 v141, v139
	v_mul_f32_e32 v139, 0x4b800000, v142
	v_pk_mul_f32 v[144:145], v[140:141], s[20:21] op_sel_hi:[1,0]
	s_nop 0
	v_cndmask_b32_e64 v140, v140, v144, s[6:7]
	v_cmp_gt_f32_e64 s[6:7], s54, v142
	v_cndmask_b32_e32 v141, v141, v145, vcc
	v_cmp_gt_f32_e32 vcc, s54, v143
	v_cndmask_b32_e64 v139, v142, v139, s[6:7]
	v_rsq_f32_e32 v142, v139
	v_mul_f32_e32 v139, 0x4b800000, v143
	v_cndmask_b32_e32 v139, v143, v139, vcc
	v_rsq_f32_e32 v143, v139
	v_pk_fma_f32 v[120:121], v[120:121], v[140:141], v[170:171] op_sel_hi:[1,1,0]
	v_pk_fma_f32 v[124:125], v[124:125], v[140:141], v[168:169] op_sel_hi:[1,1,0]
	v_pk_fma_f32 v[112:113], v[112:113], v[140:141], v[166:167] op_sel_hi:[1,1,0]
	v_pk_mul_f32 v[144:145], v[142:143], s[20:21] op_sel_hi:[1,0]
	v_pk_fma_f32 v[116:117], v[116:117], v[140:141], v[138:139] op_sel_hi:[1,1,0]
	v_cndmask_b32_e32 v143, v143, v145, vcc
	v_cndmask_b32_e64 v142, v142, v144, s[6:7]
	v_pk_fma_f32 v[122:123], v[122:123], v[142:143], v[170:171] op_sel_hi:[1,1,0]
	v_pk_fma_f32 v[126:127], v[126:127], v[142:143], v[168:169] op_sel_hi:[1,1,0]
	v_pk_fma_f32 v[114:115], v[114:115], v[142:143], v[166:167] op_sel_hi:[1,1,0]
	v_pk_fma_f32 v[118:119], v[118:119], v[142:143], v[138:139] op_sel_hi:[1,1,0]
	v_lshl_add_u64 v[140:141], v[160:161], 2, s[0:1]
	v_lshl_add_u64 v[142:143], v[152:153], 2, s[0:1]
	v_mov_b32_e32 v140, v184
	v_lshl_add_u64 v[144:145], v[162:163], 2, s[0:1]
	v_mov_b32_e32 v141, v185
	s_waitcnt vmcnt(0)
	v_pk_fma_f32 v[140:141], v[140:141], s[16:17], v[172:173] op_sel_hi:[1,0,0]
	s_nop 0
	v_mul_f32_e32 v139, 0x4b800000, v140
	v_cmp_gt_f32_e64 s[6:7], s54, v140
	v_cmp_gt_f32_e32 vcc, s54, v141
	s_nop 0
	v_cndmask_b32_e64 v139, v140, v139, s[6:7]
	v_rsq_f32_e32 v140, v139
	v_mul_f32_e32 v139, 0x4b800000, v141
	v_cndmask_b32_e32 v139, v141, v139, vcc
	v_rsq_f32_e32 v141, v139
	s_nop 0
	v_pk_mul_f32 v[142:143], v[140:141], s[20:21] op_sel_hi:[1,0]
	s_nop 0
	v_cndmask_b32_e32 v141, v141, v143, vcc
	v_cndmask_b32_e64 v140, v140, v142, s[6:7]
	v_lshl_add_u64 v[142:143], v[164:165], 2, s[0:1]
	v_mov_b32_e32 v142, v186
	v_pk_fma_f32 v[104:105], v[104:105], v[140:141], v[170:171] op_sel_hi:[1,1,0]
	v_mov_b32_e32 v143, v187
	v_pk_fma_f32 v[108:109], v[108:109], v[140:141], v[168:169] op_sel_hi:[1,1,0]
	v_pk_fma_f32 v[96:97], v[96:97], v[140:141], v[166:167] op_sel_hi:[1,1,0]
	s_waitcnt vmcnt(0)
; __device__ __forceinline__ void norm_fix(f32x4 (&acc)[4][4], const float* rowss, const float* shW, int N, int brow, int bcol,
;                                          int wr, int wc, int fr, int fq) {
;   int mr = brow >> 12;
;   float sw[4];
; #pragma unroll
;   for (int n = 0; n < 4; n++) sw[n] = shW[(size_t)mr * N + bcol + (n >> 1) * 128 + wc * 32 + (n & 1) * 16 + fr];
; #pragma unroll
;   for (int m = 0; m < 4; m++)
; #pragma unroll
;     for (int j = 0; j < 4; j++) {
;       float rs = rsqrtf(rowss[brow + wr * 64 + m * 16 + fq * 4 + j] * (1.f / D) + 1e-6f);
; #pragma unroll
;       for (int n = 0; n < 4; n++) acc[m][n][j] = acc[m][n][j] * rs + sw[n];
;     }
; }
	v_pk_fma_f32 v[142:143], v[142:143], s[16:17], v[172:173] op_sel_hi:[1,0,0]
	s_nop 0
	v_mul_f32_e32 v139, 0x4b800000, v142
	v_cmp_gt_f32_e64 s[6:7], s54, v142
	v_cmp_gt_f32_e32 vcc, s54, v143
	s_nop 0
	v_cndmask_b32_e64 v139, v142, v139, s[6:7]
	v_rsq_f32_e32 v142, v139
	v_mul_f32_e32 v139, 0x4b800000, v143
	v_cndmask_b32_e32 v139, v143, v139, vcc
	v_rsq_f32_e32 v143, v139
	v_pk_fma_f32 v[100:101], v[100:101], v[140:141], v[138:139] op_sel_hi:[1,1,0]
	v_lshl_add_u64 v[140:141], v[156:157], 2, s[0:1]
	v_mov_b32_e32 v140, v188
	v_pk_mul_f32 v[144:145], v[142:143], s[20:21] op_sel_hi:[1,0]
	s_nop 0
	v_cndmask_b32_e32 v143, v143, v145, vcc
	v_cndmask_b32_e64 v142, v142, v144, s[6:7]
	v_pk_fma_f32 v[106:107], v[106:107], v[142:143], v[170:171] op_sel_hi:[1,1,0]
	v_pk_fma_f32 v[110:111], v[110:111], v[142:143], v[168:169] op_sel_hi:[1,1,0]
	v_pk_fma_f32 v[98:99], v[98:99], v[142:143], v[166:167] op_sel_hi:[1,1,0]
	v_pk_fma_f32 v[102:103], v[102:103], v[142:143], v[138:139] op_sel_hi:[1,1,0]
	v_lshl_add_u64 v[142:143], v[148:149], 2, s[0:1]
	v_mov_b32_e32 v141, v189
	v_lshl_add_u64 v[144:145], v[150:151], 2, s[0:1]
	s_waitcnt vmcnt(0)
	v_pk_fma_f32 v[140:141], v[140:141], s[16:17], v[172:173] op_sel_hi:[1,0,0]
	s_nop 0
	v_mul_f32_e32 v139, 0x4b800000, v140
	v_cmp_gt_f32_e64 s[6:7], s54, v140
	v_cmp_gt_f32_e32 vcc, s54, v141
	s_nop 0
	v_cndmask_b32_e64 v139, v140, v139, s[6:7]
	v_rsq_f32_e32 v140, v139
	v_mul_f32_e32 v139, 0x4b800000, v141
	v_cndmask_b32_e32 v139, v141, v139, vcc
	v_rsq_f32_e32 v141, v139
	s_nop 0
	v_pk_mul_f32 v[142:143], v[140:141], s[20:21] op_sel_hi:[1,0]
	s_nop 0
	v_cndmask_b32_e32 v141, v141, v143, vcc
	v_cndmask_b32_e64 v140, v140, v142, s[6:7]
	v_lshl_add_u64 v[142:143], v[158:159], 2, s[0:1]
	v_mov_b32_e32 v142, v190
	v_pk_fma_f32 v[88:89], v[88:89], v[140:141], v[170:171] op_sel_hi:[1,1,0]
	v_mov_b32_e32 v143, v191
	v_pk_fma_f32 v[92:93], v[92:93], v[140:141], v[168:169] op_sel_hi:[1,1,0]
	v_pk_fma_f32 v[80:81], v[80:81], v[140:141], v[166:167] op_sel_hi:[1,1,0]
	s_waitcnt vmcnt(0)
	v_pk_fma_f32 v[142:143], v[142:143], s[16:17], v[172:173] op_sel_hi:[1,0,0]
	s_nop 0
	v_mul_f32_e32 v139, 0x4b800000, v142
	v_cmp_gt_f32_e64 s[6:7], s54, v142
	v_cmp_gt_f32_e32 vcc, s54, v143
	s_nop 0
	v_cndmask_b32_e64 v139, v142, v139, s[6:7]
	v_rsq_f32_e32 v142, v139
	v_mul_f32_e32 v139, 0x4b800000, v143
	v_cndmask_b32_e32 v139, v143, v139, vcc
	v_rsq_f32_e32 v143, v139
	v_pk_fma_f32 v[84:85], v[84:85], v[140:141], v[138:139] op_sel_hi:[1,1,0]
	v_pk_mul_f32 v[144:145], v[142:143], s[20:21] op_sel_hi:[1,0]
	s_nop 0
	v_cndmask_b32_e64 v142, v142, v144, s[6:7]
	v_add_u32_e32 v144, 48, v154
	v_cndmask_b32_e32 v143, v143, v145, vcc
	v_ashrrev_i32_e32 v145, 31, v144
	v_lshl_add_u64 v[140:141], v[144:145], 2, s[0:1]
	v_pk_fma_f32 v[90:91], v[90:91], v[142:143], v[170:171] op_sel_hi:[1,1,0]
	v_pk_fma_f32 v[94:95], v[94:95], v[142:143], v[168:169] op_sel_hi:[1,1,0]
	v_pk_fma_f32 v[82:83], v[82:83], v[142:143], v[166:167] op_sel_hi:[1,1,0]
	v_pk_fma_f32 v[86:87], v[86:87], v[142:143], v[138:139] op_sel_hi:[1,1,0]
	v_mov_b32_e32 v142, v192
	v_add_u32_e32 v140, 49, v154
	v_ashrrev_i32_e32 v141, 31, v140
	v_lshl_add_u64 v[146:147], v[140:141], 2, s[0:1]
	v_mov_b32_e32 v143, v193
	s_waitcnt vmcnt(0)
	v_pk_fma_f32 v[142:143], v[142:143], s[16:17], v[172:173] op_sel_hi:[1,0,0]
	s_nop 0
	v_mul_f32_e32 v139, 0x4b800000, v142
	v_cmp_gt_f32_e64 s[6:7], s54, v142
	v_cmp_gt_f32_e32 vcc, s54, v143
	s_nop 0
	v_cndmask_b32_e64 v139, v142, v139, s[6:7]
	v_rsq_f32_e32 v142, v139
	v_mul_f32_e32 v139, 0x4b800000, v143
	v_cndmask_b32_e32 v139, v143, v139, vcc
	v_rsq_f32_e32 v143, v139
	s_nop 0
	v_pk_mul_f32 v[146:147], v[142:143], s[20:21] op_sel_hi:[1,0]
	s_nop 0
	v_cndmask_b32_e64 v174, v142, v146, s[6:7]
	v_add_u32_e32 v146, 50, v154
	v_cndmask_b32_e32 v175, v143, v147, vcc
	v_ashrrev_i32_e32 v147, 31, v146
	v_lshl_add_u64 v[142:143], v[146:147], 2, s[0:1]
	v_mov_b32_e32 v176, v194
	v_add_u32_e32 v142, 51, v154
	v_ashrrev_i32_e32 v143, 31, v142
	v_lshl_add_u64 v[180:181], v[142:143], 2, s[0:1]
	v_mov_b32_e32 v177, v195
	v_pk_fma_f32 v[72:73], v[72:73], v[174:175], v[170:171] op_sel_hi:[1,1,0]
	v_pk_fma_f32 v[76:77], v[76:77], v[174:175], v[168:169] op_sel_hi:[1,1,0]
	v_pk_fma_f32 v[64:65], v[64:65], v[174:175], v[166:167] op_sel_hi:[1,1,0]
	s_waitcnt vmcnt(0)
	v_pk_fma_f32 v[172:173], v[176:177], s[16:17], v[172:173] op_sel_hi:[1,0,0]
	s_nop 0
	v_mul_f32_e32 v139, 0x4b800000, v172
	v_cmp_gt_f32_e64 s[6:7], s54, v172
	v_cmp_gt_f32_e32 vcc, s54, v173
	s_nop 0
	v_cndmask_b32_e64 v139, v172, v139, s[6:7]
	v_rsq_f32_e32 v172, v139
	v_mul_f32_e32 v139, 0x4b800000, v173
	v_cndmask_b32_e32 v139, v173, v139, vcc
	v_rsq_f32_e32 v173, v139
	v_pk_fma_f32 v[68:69], v[68:69], v[174:175], v[138:139] op_sel_hi:[1,1,0]
	v_pk_mul_f32 v[176:177], v[172:173], s[20:21] op_sel_hi:[1,0]
	s_nop 0
	v_cndmask_b32_e32 v173, v173, v177, vcc
	v_cndmask_b32_e64 v172, v172, v176, s[6:7]
	v_pk_fma_f32 v[74:75], v[74:75], v[172:173], v[170:171] op_sel_hi:[1,1,0]
	v_pk_fma_f32 v[78:79], v[78:79], v[172:173], v[168:169] op_sel_hi:[1,1,0]
	v_pk_fma_f32 v[66:67], v[66:67], v[172:173], v[166:167] op_sel_hi:[1,1,0]
	v_pk_fma_f32 v[70:71], v[70:71], v[172:173], v[138:139] op_sel_hi:[1,1,0]
	v_mov_b64_e32 v[166:167], v[154:155]

; __device__ __forceinline__ void norm_fix(f32x4 (&acc)[4][4], const float* rowss, const float* shW, int N, int brow, int bcol,
;                                          int wr, int wc, int fr, int fq) {
;   int mr = brow >> 12;
;   float sw[4];
; #pragma unroll
;   for (int n = 0; n < 4; n++) sw[n] = shW[(size_t)mr * N + bcol + (n >> 1) * 128 + wc * 32 + (n & 1) * 16 + fr];
; #pragma unroll
;   for (int m = 0; m < 4; m++)
; #pragma unroll
;     for (int j = 0; j < 4; j++) {
;       float rs = rsqrtf(rowss[brow + wr * 64 + m * 16 + fq * 4 + j] * (1.f / D) + 1e-6f);
; #pragma unroll
;       for (int n = 0; n < 4; n++) acc[m][n][j] = acc[m][n][j] * rs + sw[n];
;     }
; }
.LBB0_873:
	s_ashr_i32 s4, s34, 12
	s_mul_hi_i32 s5, s4, 0x5800
	s_mulk_i32 s4, 0x5800
	s_add_u32 s21, s17, s4
	s_addc_u32 s25, s19, s5
	s_lshl_b64 s[4:5], s[28:29], 2
	s_add_u32 s4, s21, s4
	s_addc_u32 s5, s25, s5
	s_lshl_b32 s21, s15, 2
	s_add_u32 s4, s4, s21
	v_ashrrev_i32_e32 v65, 31, v64
	s_addc_u32 s5, s5, 0
	v_lshl_add_u64 v[66:67], v[64:65], 2, s[0:1]
	global_load_dword v96, v179, s[4:5]
	global_load_dword v94, v179, s[4:5] offset:64
	global_load_dword v92, v179, s[4:5] offset:512
	global_load_dword v90, v179, s[4:5] offset:576
	v_mov_b64_e32 v[98:99], s[16:17]
	global_load_dwordx4 v[184:187], v[66:67], off offset:64
	global_load_dwordx4 v[188:191], v[66:67], off offset:128
	global_load_dwordx4 v[192:195], v[66:67], off offset:192
	global_load_dwordx4 v[66:69], v[66:67], off
	v_add_u32_e32 v72, 16, v64
	v_ashrrev_i32_e32 v73, 31, v72
	v_add_u32_e32 v88, 18, v64
	v_add_u32_e32 v86, 19, v64
	v_add_u32_e32 v80, 32, v64
	v_ashrrev_i32_e32 v89, 31, v88
	v_ashrrev_i32_e32 v87, 31, v86
	v_ashrrev_i32_e32 v81, 31, v80
	v_lshl_add_u64 v[74:75], v[86:87], 2, s[0:1]
	v_add_u32_e32 v76, 33, v64
	v_ashrrev_i32_e32 v77, 31, v76
	v_add_u32_e32 v84, 34, v64
	v_add_u32_e32 v82, 35, v64
	v_ashrrev_i32_e32 v85, 31, v84
	v_ashrrev_i32_e32 v83, 31, v82
	s_waitcnt vmcnt(0)
	v_pk_fma_f32 v[66:67], v[66:67], s[14:15], v[98:99] op_sel_hi:[1,0,0]
	s_nop 0
	v_mul_f32_e32 v70, 0x4b800000, v66
	v_cmp_gt_f32_e64 s[4:5], s52, v66
	v_cmp_gt_f32_e32 vcc, s52, v67
	v_pk_fma_f32 v[68:69], v[68:69], s[14:15], v[98:99] op_sel_hi:[1,0,0]
	v_cndmask_b32_e64 v66, v66, v70, s[4:5]
	v_mul_f32_e32 v70, 0x4b800000, v67
	v_cndmask_b32_e32 v67, v67, v70, vcc
	v_rsq_f32_e32 v66, v66
	v_rsq_f32_e32 v67, v67
	s_nop 0
	v_pk_mul_f32 v[70:71], v[66:67], s[18:19] op_sel_hi:[1,0]
	s_nop 0
	v_cndmask_b32_e64 v66, v66, v70, s[4:5]
	v_mul_f32_e32 v70, 0x4b800000, v68
	v_cmp_gt_f32_e64 s[4:5], s52, v68
	v_cndmask_b32_e32 v67, v67, v71, vcc
	v_cmp_gt_f32_e32 vcc, s52, v69
	v_cndmask_b32_e64 v68, v68, v70, s[4:5]
	v_mul_f32_e32 v70, 0x4b800000, v69
	v_cndmask_b32_e32 v69, v69, v70, vcc
	v_rsq_f32_e32 v68, v68
	v_rsq_f32_e32 v69, v69
	v_pk_fma_f32 v[56:57], v[56:57], v[66:67], v[96:97] op_sel_hi:[1,1,0]
	v_pk_fma_f32 v[60:61], v[60:61], v[66:67], v[94:95] op_sel_hi:[1,1,0]
	v_pk_fma_f32 v[52:53], v[52:53], v[66:67], v[92:93] op_sel_hi:[1,1,0]
	v_pk_mul_f32 v[70:71], v[68:69], s[18:19] op_sel_hi:[1,0]
	v_pk_fma_f32 v[48:49], v[48:49], v[66:67], v[90:91] op_sel_hi:[1,1,0]
	v_cndmask_b32_e32 v69, v69, v71, vcc
	v_cndmask_b32_e64 v68, v68, v70, s[4:5]
	v_pk_fma_f32 v[58:59], v[58:59], v[68:69], v[96:97] op_sel_hi:[1,1,0]
	v_pk_fma_f32 v[62:63], v[62:63], v[68:69], v[94:95] op_sel_hi:[1,1,0]
	v_pk_fma_f32 v[54:55], v[54:55], v[68:69], v[92:93] op_sel_hi:[1,1,0]
	v_pk_fma_f32 v[50:51], v[50:51], v[68:69], v[90:91] op_sel_hi:[1,1,0]
	v_add_u32_e32 v68, 17, v64
	v_ashrrev_i32_e32 v69, 31, v68
	v_lshl_add_u64 v[66:67], v[72:73], 2, s[0:1]
	v_lshl_add_u64 v[70:71], v[68:69], 2, s[0:1]
	v_mov_b32_e32 v66, v184
	s_nop 0
	v_mov_b32_e32 v67, v185
	s_waitcnt vmcnt(0)
	v_pk_fma_f32 v[66:67], v[66:67], s[14:15], v[98:99] op_sel_hi:[1,0,0]
	s_nop 0
	v_mul_f32_e32 v70, 0x4b800000, v66
	v_cmp_gt_f32_e64 s[4:5], s52, v66
	v_cmp_gt_f32_e32 vcc, s52, v67
	s_nop 0
	v_cndmask_b32_e64 v66, v66, v70, s[4:5]
	v_mul_f32_e32 v70, 0x4b800000, v67
	v_cndmask_b32_e32 v67, v67, v70, vcc
	v_rsq_f32_e32 v66, v66
	v_rsq_f32_e32 v67, v67
	s_nop 0
	v_pk_mul_f32 v[70:71], v[66:67], s[18:19] op_sel_hi:[1,0]
	s_nop 0
	v_cndmask_b32_e32 v67, v67, v71, vcc
	v_cndmask_b32_e64 v66, v66, v70, s[4:5]
	v_lshl_add_u64 v[70:71], v[88:89], 2, s[0:1]
	v_pk_fma_f32 v[40:41], v[40:41], v[66:67], v[96:97] op_sel_hi:[1,1,0]
	v_pk_fma_f32 v[44:45], v[44:45], v[66:67], v[94:95] op_sel_hi:[1,1,0]
	v_pk_fma_f32 v[36:37], v[36:37], v[66:67], v[92:93] op_sel_hi:[1,1,0]
	v_pk_fma_f32 v[32:33], v[32:33], v[66:67], v[90:91] op_sel_hi:[1,1,0]
	v_lshl_add_u64 v[66:67], v[80:81], 2, s[0:1]
	v_mov_b32_e32 v70, v186
	s_nop 0
	v_mov_b32_e32 v66, v188
	s_nop 0
	v_mov_b32_e32 v71, v187
	s_waitcnt vmcnt(0)
; __device__ __forceinline__ void norm_fix(f32x4 (&acc)[4][4], const float* rowss, const float* shW, int N, int brow, int bcol,
;                                          int wr, int wc, int fr, int fq) {
;   int mr = brow >> 12;
;   float sw[4];
; #pragma unroll
;   for (int n = 0; n < 4; n++) sw[n] = shW[(size_t)mr * N + bcol + (n >> 1) * 128 + wc * 32 + (n & 1) * 16 + fr];
; #pragma unroll
;   for (int m = 0; m < 4; m++)
; #pragma unroll
;     for (int j = 0; j < 4; j++) {
;       float rs = rsqrtf(rowss[brow + wr * 64 + m * 16 + fq * 4 + j] * (1.f / D) + 1e-6f);
; #pragma unroll
;       for (int n = 0; n < 4; n++) acc[m][n][j] = acc[m][n][j] * rs + sw[n];
;     }
; }
	v_pk_fma_f32 v[70:71], v[70:71], s[14:15], v[98:99] op_sel_hi:[1,0,0]
	s_nop 0
	v_mul_f32_e32 v74, 0x4b800000, v70
	v_cmp_gt_f32_e64 s[4:5], s52, v70
	v_cmp_gt_f32_e32 vcc, s52, v71
	s_nop 0
	v_cndmask_b32_e64 v70, v70, v74, s[4:5]
	v_mul_f32_e32 v74, 0x4b800000, v71
	v_cndmask_b32_e32 v71, v71, v74, vcc
	v_rsq_f32_e32 v70, v70
	v_rsq_f32_e32 v71, v71
	s_nop 0
	v_pk_mul_f32 v[74:75], v[70:71], s[18:19] op_sel_hi:[1,0]
	s_nop 0
	v_cndmask_b32_e32 v71, v71, v75, vcc
	v_cndmask_b32_e64 v70, v70, v74, s[4:5]
	v_pk_fma_f32 v[42:43], v[42:43], v[70:71], v[96:97] op_sel_hi:[1,1,0]
	v_pk_fma_f32 v[46:47], v[46:47], v[70:71], v[94:95] op_sel_hi:[1,1,0]
	v_pk_fma_f32 v[38:39], v[38:39], v[70:71], v[92:93] op_sel_hi:[1,1,0]
	v_pk_fma_f32 v[34:35], v[34:35], v[70:71], v[90:91] op_sel_hi:[1,1,0]
	v_lshl_add_u64 v[70:71], v[76:77], 2, s[0:1]
	v_mov_b32_e32 v67, v189
	v_lshl_add_u64 v[74:75], v[82:83], 2, s[0:1]
	s_waitcnt vmcnt(0)
	v_pk_fma_f32 v[66:67], v[66:67], s[14:15], v[98:99] op_sel_hi:[1,0,0]
	s_nop 0
	v_mul_f32_e32 v70, 0x4b800000, v66
	v_cmp_gt_f32_e64 s[4:5], s52, v66
	v_cmp_gt_f32_e32 vcc, s52, v67
	s_nop 0
	v_cndmask_b32_e64 v66, v66, v70, s[4:5]
	v_mul_f32_e32 v70, 0x4b800000, v67
	v_cndmask_b32_e32 v67, v67, v70, vcc
	v_rsq_f32_e32 v66, v66
	v_rsq_f32_e32 v67, v67
	s_nop 0
	v_pk_mul_f32 v[70:71], v[66:67], s[18:19] op_sel_hi:[1,0]
	s_nop 0
	v_cndmask_b32_e32 v67, v67, v71, vcc
	v_cndmask_b32_e64 v66, v66, v70, s[4:5]
	v_lshl_add_u64 v[70:71], v[84:85], 2, s[0:1]
	v_mov_b32_e32 v70, v190
	v_pk_fma_f32 v[24:25], v[24:25], v[66:67], v[96:97] op_sel_hi:[1,1,0]
	v_mov_b32_e32 v71, v191
	v_pk_fma_f32 v[28:29], v[28:29], v[66:67], v[94:95] op_sel_hi:[1,1,0]
	v_pk_fma_f32 v[20:21], v[20:21], v[66:67], v[92:93] op_sel_hi:[1,1,0]
	v_pk_fma_f32 v[16:17], v[16:17], v[66:67], v[90:91] op_sel_hi:[1,1,0]
	s_waitcnt vmcnt(0)
	v_pk_fma_f32 v[70:71], v[70:71], s[14:15], v[98:99] op_sel_hi:[1,0,0]
	s_nop 0
	v_mul_f32_e32 v74, 0x4b800000, v70
	v_cmp_gt_f32_e64 s[4:5], s52, v70
	v_cmp_gt_f32_e32 vcc, s52, v71
	s_nop 0
	v_cndmask_b32_e64 v70, v70, v74, s[4:5]
	v_mul_f32_e32 v74, 0x4b800000, v71
	v_cndmask_b32_e32 v71, v71, v74, vcc
	v_rsq_f32_e32 v70, v70
	v_rsq_f32_e32 v71, v71
	s_nop 0
	v_pk_mul_f32 v[74:75], v[70:71], s[18:19] op_sel_hi:[1,0]
	s_nop 0
	v_cndmask_b32_e32 v71, v71, v75, vcc
	v_cndmask_b32_e64 v70, v70, v74, s[4:5]
	v_pk_fma_f32 v[26:27], v[26:27], v[70:71], v[96:97] op_sel_hi:[1,1,0]
	v_pk_fma_f32 v[30:31], v[30:31], v[70:71], v[94:95] op_sel_hi:[1,1,0]
	v_pk_fma_f32 v[22:23], v[22:23], v[70:71], v[92:93] op_sel_hi:[1,1,0]
	v_pk_fma_f32 v[18:19], v[18:19], v[70:71], v[90:91] op_sel_hi:[1,1,0]
	v_add_u32_e32 v70, 48, v64
	v_ashrrev_i32_e32 v71, 31, v70
	v_lshl_add_u64 v[66:67], v[70:71], 2, s[0:1]
	v_mov_b32_e32 v74, v192
	v_add_u32_e32 v66, 49, v64
	v_ashrrev_i32_e32 v67, 31, v66
	v_lshl_add_u64 v[78:79], v[66:67], 2, s[0:1]
	v_mov_b32_e32 v75, v193
	s_waitcnt vmcnt(0)
	v_pk_fma_f32 v[74:75], v[74:75], s[14:15], v[98:99] op_sel_hi:[1,0,0]
	s_nop 0
	v_mul_f32_e32 v78, 0x4b800000, v74
	v_cmp_gt_f32_e64 s[4:5], s52, v74
	v_cmp_gt_f32_e32 vcc, s52, v75
	s_nop 0
	v_cndmask_b32_e64 v74, v74, v78, s[4:5]
	v_mul_f32_e32 v78, 0x4b800000, v75
	v_cndmask_b32_e32 v75, v75, v78, vcc
	v_rsq_f32_e32 v74, v74
	v_rsq_f32_e32 v75, v75
	s_nop 0
	v_pk_mul_f32 v[78:79], v[74:75], s[18:19] op_sel_hi:[1,0]
	s_nop 0
	v_cndmask_b32_e64 v100, v74, v78, s[4:5]
	v_add_u32_e32 v78, 50, v64
	v_cndmask_b32_e32 v101, v75, v79, vcc
	v_ashrrev_i32_e32 v79, 31, v78
	v_lshl_add_u64 v[74:75], v[78:79], 2, s[0:1]
	v_mov_b32_e32 v102, v194
	v_add_u32_e32 v74, 51, v64
	v_ashrrev_i32_e32 v75, 31, v74
	v_lshl_add_u64 v[104:105], v[74:75], 2, s[0:1]
	v_mov_b32_e32 v103, v195
	v_pk_fma_f32 v[8:9], v[8:9], v[100:101], v[96:97] op_sel_hi:[1,1,0]
	v_pk_fma_f32 v[12:13], v[12:13], v[100:101], v[94:95] op_sel_hi:[1,1,0]
	v_pk_fma_f32 v[0:1], v[0:1], v[100:101], v[92:93] op_sel_hi:[1,1,0]
	s_waitcnt vmcnt(0)
	v_pk_fma_f32 v[98:99], v[102:103], s[14:15], v[98:99] op_sel_hi:[1,0,0]
	s_nop 0
	v_mul_f32_e32 v91, 0x4b800000, v98
	v_cmp_gt_f32_e64 s[4:5], s52, v98
	v_cmp_gt_f32_e32 vcc, s52, v99
	s_nop 0
	v_cndmask_b32_e64 v91, v98, v91, s[4:5]
	v_rsq_f32_e32 v98, v91
	v_mul_f32_e32 v91, 0x4b800000, v99
	v_cndmask_b32_e32 v91, v99, v91, vcc
	v_rsq_f32_e32 v99, v91
	v_pk_fma_f32 v[4:5], v[4:5], v[100:101], v[90:91] op_sel_hi:[1,1,0]
	v_pk_mul_f32 v[102:103], v[98:99], s[18:19] op_sel_hi:[1,0]
	s_nop 0
	v_cndmask_b32_e32 v99, v99, v103, vcc
	v_cndmask_b32_e64 v98, v98, v102, s[4:5]
	v_pk_fma_f32 v[10:11], v[10:11], v[98:99], v[96:97] op_sel_hi:[1,1,0]
	v_pk_fma_f32 v[14:15], v[14:15], v[98:99], v[94:95] op_sel_hi:[1,1,0]
	v_pk_fma_f32 v[2:3], v[2:3], v[98:99], v[92:93] op_sel_hi:[1,1,0]
	v_pk_fma_f32 v[6:7], v[6:7], v[98:99], v[90:91] op_sel_hi:[1,1,0]
	v_mov_b64_e32 v[90:91], v[64:65]

; __device__ __forceinline__ void norm_fix(f32x4 (&acc)[4][4], const float* rowss, const float* shW, int N, int brow, int bcol,
;                                          int wr, int wc, int fr, int fq) {
;   int mr = brow >> 12;
;   float sw[4];
; #pragma unroll
;   for (int n = 0; n < 4; n++) sw[n] = shW[(size_t)mr * N + bcol + (n >> 1) * 128 + wc * 32 + (n & 1) * 16 + fr];
; #pragma unroll
;   for (int m = 0; m < 4; m++)
; #pragma unroll
;     for (int j = 0; j < 4; j++) {
;       float rs = rsqrtf(rowss[brow + wr * 64 + m * 16 + fq * 4 + j] * (1.f / D) + 1e-6f);
; #pragma unroll
;       for (int n = 0; n < 4; n++) acc[m][n][j] = acc[m][n][j] * rs + sw[n];
;     }
.LBB0_888:
	s_ashr_i32 s4, s30, 12
	s_mul_hi_i32 s5, s4, 0x5800
	s_mulk_i32 s4, 0x5800
	s_add_u32 s21, s17, s4
	s_addc_u32 s25, s19, s5
	s_lshl_b64 s[4:5], s[28:29], 2
	s_add_u32 s4, s21, s4
	s_addc_u32 s5, s25, s5
	s_lshl_b32 s21, s15, 2
	s_add_u32 s4, s4, s21
	v_ashrrev_i32_e32 v155, 31, v154
	s_addc_u32 s5, s5, 0
	v_lshl_add_u64 v[140:141], v[154:155], 2, s[0:1]
	global_load_dword v170, v179, s[4:5]
	global_load_dword v168, v179, s[4:5] offset:64
	global_load_dword v166, v179, s[4:5] offset:512
	global_load_dword v138, v179, s[4:5] offset:576
	v_mov_b64_e32 v[172:173], s[16:17]
	global_load_dwordx4 v[184:187], v[140:141], off offset:64
	global_load_dwordx4 v[188:191], v[140:141], off offset:128
	global_load_dwordx4 v[192:195], v[140:141], off offset:192
	global_load_dwordx4 v[140:143], v[140:141], off
	v_add_u32_e32 v160, 16, v154
	v_add_u32_e32 v152, 17, v154
	v_ashrrev_i32_e32 v161, 31, v160
	v_ashrrev_i32_e32 v153, 31, v152
	v_add_u32_e32 v164, 18, v154
	v_add_u32_e32 v162, 19, v154
	v_ashrrev_i32_e32 v165, 31, v164
	v_ashrrev_i32_e32 v163, 31, v162
	v_add_u32_e32 v156, 32, v154
	v_add_u32_e32 v148, 33, v154
	v_ashrrev_i32_e32 v157, 31, v156
	v_ashrrev_i32_e32 v149, 31, v148
	v_add_u32_e32 v158, 34, v154
	v_add_u32_e32 v150, 35, v154
	v_ashrrev_i32_e32 v159, 31, v158
	v_ashrrev_i32_e32 v151, 31, v150
	s_waitcnt vmcnt(0)
	v_pk_fma_f32 v[140:141], v[140:141], s[14:15], v[172:173] op_sel_hi:[1,0,0]
	s_nop 0
	v_mul_f32_e32 v139, 0x4b800000, v140
	v_cmp_gt_f32_e64 s[4:5], s52, v140
	v_cmp_gt_f32_e32 vcc, s52, v141
	v_pk_fma_f32 v[142:143], v[142:143], s[14:15], v[172:173] op_sel_hi:[1,0,0]
	v_cndmask_b32_e64 v139, v140, v139, s[4:5]
	v_rsq_f32_e32 v140, v139
	v_mul_f32_e32 v139, 0x4b800000, v141
	v_cndmask_b32_e32 v139, v141, v139, vcc
	v_rsq_f32_e32 v141, v139
	v_mul_f32_e32 v139, 0x4b800000, v142
	v_pk_mul_f32 v[144:145], v[140:141], s[18:19] op_sel_hi:[1,0]
	s_nop 0
	v_cndmask_b32_e64 v140, v140, v144, s[4:5]
	v_cmp_gt_f32_e64 s[4:5], s52, v142
	v_cndmask_b32_e32 v141, v141, v145, vcc
	v_cmp_gt_f32_e32 vcc, s52, v143
	v_cndmask_b32_e64 v139, v142, v139, s[4:5]
	v_rsq_f32_e32 v142, v139
	v_mul_f32_e32 v139, 0x4b800000, v143
	v_cndmask_b32_e32 v139, v143, v139, vcc
	v_rsq_f32_e32 v143, v139
	v_pk_fma_f32 v[120:121], v[120:121], v[140:141], v[170:171] op_sel_hi:[1,1,0]
	v_pk_fma_f32 v[124:125], v[124:125], v[140:141], v[168:169] op_sel_hi:[1,1,0]
	v_pk_fma_f32 v[112:113], v[112:113], v[140:141], v[166:167] op_sel_hi:[1,1,0]
	v_pk_mul_f32 v[144:145], v[142:143], s[18:19] op_sel_hi:[1,0]
	v_pk_fma_f32 v[116:117], v[116:117], v[140:141], v[138:139] op_sel_hi:[1,1,0]
	v_cndmask_b32_e32 v143, v143, v145, vcc
	v_cndmask_b32_e64 v142, v142, v144, s[4:5]
	v_pk_fma_f32 v[122:123], v[122:123], v[142:143], v[170:171] op_sel_hi:[1,1,0]
	v_pk_fma_f32 v[126:127], v[126:127], v[142:143], v[168:169] op_sel_hi:[1,1,0]
	v_pk_fma_f32 v[114:115], v[114:115], v[142:143], v[166:167] op_sel_hi:[1,1,0]
	v_pk_fma_f32 v[118:119], v[118:119], v[142:143], v[138:139] op_sel_hi:[1,1,0]
	v_lshl_add_u64 v[140:141], v[160:161], 2, s[0:1]
	v_lshl_add_u64 v[142:143], v[152:153], 2, s[0:1]
	v_mov_b32_e32 v140, v184
	v_lshl_add_u64 v[144:145], v[162:163], 2, s[0:1]
	v_mov_b32_e32 v141, v185
	s_waitcnt vmcnt(0)
	v_pk_fma_f32 v[140:141], v[140:141], s[14:15], v[172:173] op_sel_hi:[1,0,0]
	s_nop 0
	v_mul_f32_e32 v139, 0x4b800000, v140
	v_cmp_gt_f32_e64 s[4:5], s52, v140
	v_cmp_gt_f32_e32 vcc, s52, v141
	s_nop 0
	v_cndmask_b32_e64 v139, v140, v139, s[4:5]
	v_rsq_f32_e32 v140, v139
	v_mul_f32_e32 v139, 0x4b800000, v141
	v_cndmask_b32_e32 v139, v141, v139, vcc
	v_rsq_f32_e32 v141, v139
	s_nop 0
	v_pk_mul_f32 v[142:143], v[140:141], s[18:19] op_sel_hi:[1,0]
	s_nop 0
	v_cndmask_b32_e32 v141, v141, v143, vcc
	v_cndmask_b32_e64 v140, v140, v142, s[4:5]
	v_lshl_add_u64 v[142:143], v[164:165], 2, s[0:1]
	v_mov_b32_e32 v142, v186
	v_pk_fma_f32 v[104:105], v[104:105], v[140:141], v[170:171] op_sel_hi:[1,1,0]
	v_mov_b32_e32 v143, v187
	v_pk_fma_f32 v[108:109], v[108:109], v[140:141], v[168:169] op_sel_hi:[1,1,0]
	v_pk_fma_f32 v[96:97], v[96:97], v[140:141], v[166:167] op_sel_hi:[1,1,0]
	s_waitcnt vmcnt(0)
; __device__ __forceinline__ void norm_fix(f32x4 (&acc)[4][4], const float* rowss, const float* shW, int N, int brow, int bcol,
;                                          int wr, int wc, int fr, int fq) {
;   int mr = brow >> 12;
;   float sw[4];
; #pragma unroll
;   for (int n = 0; n < 4; n++) sw[n] = shW[(size_t)mr * N + bcol + (n >> 1) * 128 + wc * 32 + (n & 1) * 16 + fr];
; #pragma unroll
;   for (int m = 0; m < 4; m++)
; #pragma unroll
;     for (int j = 0; j < 4; j++) {
;       float rs = rsqrtf(rowss[brow + wr * 64 + m * 16 + fq * 4 + j] * (1.f / D) + 1e-6f);
; #pragma unroll
;       for (int n = 0; n < 4; n++) acc[m][n][j] = acc[m][n][j] * rs + sw[n];
;     }
	v_pk_fma_f32 v[142:143], v[142:143], s[14:15], v[172:173] op_sel_hi:[1,0,0]
	s_nop 0
	v_mul_f32_e32 v139, 0x4b800000, v142
	v_cmp_gt_f32_e64 s[4:5], s52, v142
	v_cmp_gt_f32_e32 vcc, s52, v143
	s_nop 0
	v_cndmask_b32_e64 v139, v142, v139, s[4:5]
	v_rsq_f32_e32 v142, v139
	v_mul_f32_e32 v139, 0x4b800000, v143
	v_cndmask_b32_e32 v139, v143, v139, vcc
	v_rsq_f32_e32 v143, v139
	v_pk_fma_f32 v[100:101], v[100:101], v[140:141], v[138:139] op_sel_hi:[1,1,0]
	v_lshl_add_u64 v[140:141], v[156:157], 2, s[0:1]
	v_mov_b32_e32 v140, v188
	v_pk_mul_f32 v[144:145], v[142:143], s[18:19] op_sel_hi:[1,0]
	s_nop 0
	v_cndmask_b32_e32 v143, v143, v145, vcc
	v_cndmask_b32_e64 v142, v142, v144, s[4:5]
	v_pk_fma_f32 v[106:107], v[106:107], v[142:143], v[170:171] op_sel_hi:[1,1,0]
	v_pk_fma_f32 v[110:111], v[110:111], v[142:143], v[168:169] op_sel_hi:[1,1,0]
	v_pk_fma_f32 v[98:99], v[98:99], v[142:143], v[166:167] op_sel_hi:[1,1,0]
	v_pk_fma_f32 v[102:103], v[102:103], v[142:143], v[138:139] op_sel_hi:[1,1,0]
	v_lshl_add_u64 v[142:143], v[148:149], 2, s[0:1]
	v_mov_b32_e32 v141, v189
	v_lshl_add_u64 v[144:145], v[150:151], 2, s[0:1]
	s_waitcnt vmcnt(0)
	v_pk_fma_f32 v[140:141], v[140:141], s[14:15], v[172:173] op_sel_hi:[1,0,0]
	s_nop 0
	v_mul_f32_e32 v139, 0x4b800000, v140
	v_cmp_gt_f32_e64 s[4:5], s52, v140
	v_cmp_gt_f32_e32 vcc, s52, v141
	s_nop 0
	v_cndmask_b32_e64 v139, v140, v139, s[4:5]
	v_rsq_f32_e32 v140, v139
	v_mul_f32_e32 v139, 0x4b800000, v141
	v_cndmask_b32_e32 v139, v141, v139, vcc
	v_rsq_f32_e32 v141, v139
	s_nop 0
	v_pk_mul_f32 v[142:143], v[140:141], s[18:19] op_sel_hi:[1,0]
	s_nop 0
	v_cndmask_b32_e32 v141, v141, v143, vcc
	v_cndmask_b32_e64 v140, v140, v142, s[4:5]
	v_lshl_add_u64 v[142:143], v[158:159], 2, s[0:1]
	v_mov_b32_e32 v142, v190
	v_pk_fma_f32 v[88:89], v[88:89], v[140:141], v[170:171] op_sel_hi:[1,1,0]
	v_mov_b32_e32 v143, v191
	v_pk_fma_f32 v[92:93], v[92:93], v[140:141], v[168:169] op_sel_hi:[1,1,0]
	v_pk_fma_f32 v[80:81], v[80:81], v[140:141], v[166:167] op_sel_hi:[1,1,0]
	s_waitcnt vmcnt(0)
	v_pk_fma_f32 v[142:143], v[142:143], s[14:15], v[172:173] op_sel_hi:[1,0,0]
	s_nop 0
	v_mul_f32_e32 v139, 0x4b800000, v142
	v_cmp_gt_f32_e64 s[4:5], s52, v142
	v_cmp_gt_f32_e32 vcc, s52, v143
	s_nop 0
	v_cndmask_b32_e64 v139, v142, v139, s[4:5]
	v_rsq_f32_e32 v142, v139
	v_mul_f32_e32 v139, 0x4b800000, v143
	v_cndmask_b32_e32 v139, v143, v139, vcc
	v_rsq_f32_e32 v143, v139
	v_pk_fma_f32 v[84:85], v[84:85], v[140:141], v[138:139] op_sel_hi:[1,1,0]
	v_pk_mul_f32 v[144:145], v[142:143], s[18:19] op_sel_hi:[1,0]
	s_nop 0
	v_cndmask_b32_e64 v142, v142, v144, s[4:5]
	v_add_u32_e32 v144, 48, v154
	v_cndmask_b32_e32 v143, v143, v145, vcc
	v_ashrrev_i32_e32 v145, 31, v144
	v_lshl_add_u64 v[140:141], v[144:145], 2, s[0:1]
	v_pk_fma_f32 v[90:91], v[90:91], v[142:143], v[170:171] op_sel_hi:[1,1,0]
	v_pk_fma_f32 v[94:95], v[94:95], v[142:143], v[168:169] op_sel_hi:[1,1,0]
	v_pk_fma_f32 v[82:83], v[82:83], v[142:143], v[166:167] op_sel_hi:[1,1,0]
	v_pk_fma_f32 v[86:87], v[86:87], v[142:143], v[138:139] op_sel_hi:[1,1,0]
	v_mov_b32_e32 v142, v192
	v_add_u32_e32 v140, 49, v154
	v_ashrrev_i32_e32 v141, 31, v140
	v_lshl_add_u64 v[146:147], v[140:141], 2, s[0:1]
	v_mov_b32_e32 v143, v193
	s_waitcnt vmcnt(0)
	v_pk_fma_f32 v[142:143], v[142:143], s[14:15], v[172:173] op_sel_hi:[1,0,0]
	s_nop 0
	v_mul_f32_e32 v139, 0x4b800000, v142
	v_cmp_gt_f32_e64 s[4:5], s52, v142
	v_cmp_gt_f32_e32 vcc, s52, v143
	s_nop 0
	v_cndmask_b32_e64 v139, v142, v139, s[4:5]
	v_rsq_f32_e32 v142, v139
	v_mul_f32_e32 v139, 0x4b800000, v143
	v_cndmask_b32_e32 v139, v143, v139, vcc
	v_rsq_f32_e32 v143, v139
	s_nop 0
	v_pk_mul_f32 v[146:147], v[142:143], s[18:19] op_sel_hi:[1,0]
	s_nop 0
	v_cndmask_b32_e64 v174, v142, v146, s[4:5]
	v_add_u32_e32 v146, 50, v154
	v_cndmask_b32_e32 v175, v143, v147, vcc
	v_ashrrev_i32_e32 v147, 31, v146
	v_lshl_add_u64 v[142:143], v[146:147], 2, s[0:1]
	v_mov_b32_e32 v176, v194
	v_add_u32_e32 v142, 51, v154
	v_ashrrev_i32_e32 v143, 31, v142
	v_lshl_add_u64 v[180:181], v[142:143], 2, s[0:1]
	v_mov_b32_e32 v177, v195
	v_pk_fma_f32 v[72:73], v[72:73], v[174:175], v[170:171] op_sel_hi:[1,1,0]
	v_pk_fma_f32 v[76:77], v[76:77], v[174:175], v[168:169] op_sel_hi:[1,1,0]
	v_pk_fma_f32 v[64:65], v[64:65], v[174:175], v[166:167] op_sel_hi:[1,1,0]
	s_waitcnt vmcnt(0)
	v_pk_fma_f32 v[172:173], v[176:177], s[14:15], v[172:173] op_sel_hi:[1,0,0]
	s_nop 0
	v_mul_f32_e32 v139, 0x4b800000, v172
	v_cmp_gt_f32_e64 s[4:5], s52, v172
	v_cmp_gt_f32_e32 vcc, s52, v173
	s_nop 0
	v_cndmask_b32_e64 v139, v172, v139, s[4:5]
	v_rsq_f32_e32 v172, v139
	v_mul_f32_e32 v139, 0x4b800000, v173
	v_cndmask_b32_e32 v139, v173, v139, vcc
	v_rsq_f32_e32 v173, v139
	v_pk_fma_f32 v[68:69], v[68:69], v[174:175], v[138:139] op_sel_hi:[1,1,0]
	v_pk_mul_f32 v[176:177], v[172:173], s[18:19] op_sel_hi:[1,0]
	s_nop 0
	v_cndmask_b32_e32 v173, v173, v177, vcc
	v_cndmask_b32_e64 v172, v172, v176, s[4:5]
	v_pk_fma_f32 v[74:75], v[74:75], v[172:173], v[170:171] op_sel_hi:[1,1,0]
	v_pk_fma_f32 v[78:79], v[78:79], v[172:173], v[168:169] op_sel_hi:[1,1,0]
	v_pk_fma_f32 v[66:67], v[66:67], v[172:173], v[166:167] op_sel_hi:[1,1,0]
	v_pk_fma_f32 v[70:71], v[70:71], v[172:173], v[138:139] op_sel_hi:[1,1,0]
	v_mov_b64_e32 v[166:167], v[154:155]
